# P0 weight-copy items (w_in, w_q_up, w_kv_up variants): 32 serial load round trips per item replaced by batched loads with one wait
# speedup vs baseline: 1.0223x; 1.0223x over previous
.LBB0_39:
	v_lshl_add_u64 v[84:85], v[82:83], 0, s[4:5]
	global_load_dword v200, v[84:85], off
	v_lshl_add_u64 v[84:85], v[80:81], 0, s[4:5]
	global_load_dword v201, v[84:85], off
	v_lshl_add_u64 v[84:85], v[78:79], 0, s[4:5]
	global_load_dword v202, v[84:85], off
	v_lshl_add_u64 v[84:85], v[76:77], 0, s[4:5]
	global_load_dword v203, v[84:85], off
	v_lshl_add_u64 v[84:85], v[74:75], 0, s[4:5]
	global_load_dword v204, v[84:85], off
	v_lshl_add_u64 v[84:85], v[72:73], 0, s[4:5]
	global_load_dword v205, v[84:85], off
	v_lshl_add_u64 v[84:85], v[70:71], 0, s[4:5]
	global_load_dword v206, v[84:85], off
	v_lshl_add_u64 v[84:85], v[68:69], 0, s[4:5]
	global_load_dword v207, v[84:85], off
	v_lshl_add_u64 v[84:85], v[66:67], 0, s[4:5]
	global_load_dword v208, v[84:85], off
	v_lshl_add_u64 v[84:85], v[64:65], 0, s[4:5]
	global_load_dword v209, v[84:85], off
	v_lshl_add_u64 v[84:85], v[62:63], 0, s[4:5]
	global_load_dword v210, v[84:85], off
	v_lshl_add_u64 v[84:85], v[60:61], 0, s[4:5]
	global_load_dword v211, v[84:85], off
	v_lshl_add_u64 v[84:85], v[58:59], 0, s[4:5]
	global_load_dword v212, v[84:85], off
	v_lshl_add_u64 v[84:85], v[56:57], 0, s[4:5]
	global_load_dword v213, v[84:85], off
	v_lshl_add_u64 v[84:85], v[54:55], 0, s[4:5]
	global_load_dword v214, v[84:85], off
	v_lshl_add_u64 v[84:85], v[50:51], 0, s[4:5]
	global_load_dword v215, v[84:85], off
	s_andn2_b64 vcc, exec, s[6:7]
	s_cbranch_vccnz .Ltrkv_w
	v_lshl_add_u64 v[84:85], s[10:11], 0, v[52:53]
	global_load_dword v216, v[84:85], off
	global_load_dword v217, v[84:85], off offset:8
	global_load_dword v218, v[84:85], off offset:16
	global_load_dword v219, v[84:85], off offset:24
	global_load_dword v220, v[84:85], off offset:32
	global_load_dword v221, v[84:85], off offset:40
	global_load_dword v222, v[84:85], off offset:48
	global_load_dword v223, v[84:85], off offset:56
	global_load_dword v224, v[84:85], off offset:64
	global_load_dword v225, v[84:85], off offset:72
	global_load_dword v226, v[84:85], off offset:80
	global_load_dword v227, v[84:85], off offset:88
	global_load_dword v228, v[84:85], off offset:96
	global_load_dword v229, v[84:85], off offset:104
	global_load_dword v230, v[84:85], off offset:112
	global_load_dword v231, v[84:85], off offset:120
	s_waitcnt vmcnt(0)
	v_mul_f32_e32 v200, v200, v216
	v_mul_f32_e32 v201, v201, v217
	v_mul_f32_e32 v202, v202, v218
	v_mul_f32_e32 v203, v203, v219
	v_mul_f32_e32 v204, v204, v220
	v_mul_f32_e32 v205, v205, v221
	v_mul_f32_e32 v206, v206, v222
	v_mul_f32_e32 v207, v207, v223
	v_mul_f32_e32 v208, v208, v224
	v_mul_f32_e32 v209, v209, v225
	v_mul_f32_e32 v210, v210, v226
	v_mul_f32_e32 v211, v211, v227
	v_mul_f32_e32 v212, v212, v228
	v_mul_f32_e32 v213, v213, v229
	v_mul_f32_e32 v214, v214, v230
	v_mul_f32_e32 v215, v215, v231
.Ltrkv_w:
	s_waitcnt vmcnt(0)
	ds_write_b32 v125, v200
	ds_write_b32 v125, v201 offset:264
	ds_write_b32 v125, v202 offset:528
	ds_write_b32 v125, v203 offset:792
	ds_write_b32 v125, v204 offset:1056
	ds_write_b32 v125, v205 offset:1320
	ds_write_b32 v125, v206 offset:1584
	ds_write_b32 v125, v207 offset:1848
	ds_write_b32 v125, v208 offset:2112
	ds_write_b32 v125, v209 offset:2376
	ds_write_b32 v125, v210 offset:2640
	ds_write_b32 v125, v211 offset:2904
	ds_write_b32 v125, v212 offset:3168
	ds_write_b32 v125, v213 offset:3432
	ds_write_b32 v125, v214 offset:3696
	ds_write_b32 v125, v215 offset:3960
	s_add_u32 s4, s4, 0x20000
	s_addc_u32 s5, s5, 0
	s_add_u32 s10, s10, 0x80
	s_addc_u32 s11, s11, 0
	v_add_u32_e32 v125, 0x1080, v125
	s_cmp_lg_u32 s4, 0x40000
	s_cbranch_scc1 .LBB0_39
	s_branch .LBB0_71

.LBB0_78:
	v_mov_b32_e32 v200, 0
	v_mov_b32_e32 v201, 0
	v_mov_b32_e32 v202, 0
	v_mov_b32_e32 v203, 0
	v_mov_b32_e32 v204, 0
	v_mov_b32_e32 v205, 0
	v_mov_b32_e32 v206, 0
	v_mov_b32_e32 v207, 0
	v_mov_b32_e32 v208, 0
	v_mov_b32_e32 v209, 0
	v_mov_b32_e32 v210, 0
	v_mov_b32_e32 v211, 0
	v_mov_b32_e32 v212, 0
	v_mov_b32_e32 v213, 0
	v_mov_b32_e32 v214, 0
	v_mov_b32_e32 v215, 0
	s_and_saveexec_b64 s[4:5], s[2:3]
	s_cbranch_execz .Ltrq_skip
	v_lshl_add_u64 v[84:85], v[82:83], 0, s[10:11]
	global_load_dword v200, v[84:85], off
	v_lshl_add_u64 v[84:85], v[80:81], 0, s[10:11]
	global_load_dword v201, v[84:85], off
	v_lshl_add_u64 v[84:85], v[78:79], 0, s[10:11]
	global_load_dword v202, v[84:85], off
	v_lshl_add_u64 v[84:85], v[76:77], 0, s[10:11]
	global_load_dword v203, v[84:85], off
	v_lshl_add_u64 v[84:85], v[74:75], 0, s[10:11]
	global_load_dword v204, v[84:85], off
	v_lshl_add_u64 v[84:85], v[72:73], 0, s[10:11]
	global_load_dword v205, v[84:85], off
	v_lshl_add_u64 v[84:85], v[70:71], 0, s[10:11]
	global_load_dword v206, v[84:85], off
	v_lshl_add_u64 v[84:85], v[68:69], 0, s[10:11]
	global_load_dword v207, v[84:85], off
	v_lshl_add_u64 v[84:85], v[66:67], 0, s[10:11]
	global_load_dword v208, v[84:85], off
	v_lshl_add_u64 v[84:85], v[64:65], 0, s[10:11]
	global_load_dword v209, v[84:85], off
	v_lshl_add_u64 v[84:85], v[62:63], 0, s[10:11]
	global_load_dword v210, v[84:85], off
	v_lshl_add_u64 v[84:85], v[60:61], 0, s[10:11]
	global_load_dword v211, v[84:85], off
	v_lshl_add_u64 v[84:85], v[58:59], 0, s[10:11]
	global_load_dword v212, v[84:85], off
	v_lshl_add_u64 v[84:85], v[56:57], 0, s[10:11]
	global_load_dword v213, v[84:85], off
	v_lshl_add_u64 v[84:85], v[54:55], 0, s[10:11]
	global_load_dword v214, v[84:85], off
	v_lshl_add_u64 v[84:85], v[50:51], 0, s[10:11]
	global_load_dword v215, v[84:85], off
.Ltrq_skip:
	s_or_b64 exec, exec, s[4:5]
	s_andn2_b64 vcc, exec, s[8:9]
	s_cbranch_vccnz .Ltrq_w
	v_lshl_add_u64 v[84:85], s[12:13], 0, v[52:53]
	global_load_dword v216, v[84:85], off
	global_load_dword v217, v[84:85], off offset:8
	global_load_dword v218, v[84:85], off offset:16
	global_load_dword v219, v[84:85], off offset:24
	global_load_dword v220, v[84:85], off offset:32
	global_load_dword v221, v[84:85], off offset:40
	global_load_dword v222, v[84:85], off offset:48
	global_load_dword v223, v[84:85], off offset:56
	global_load_dword v224, v[84:85], off offset:64
	global_load_dword v225, v[84:85], off offset:72
	global_load_dword v226, v[84:85], off offset:80
	global_load_dword v227, v[84:85], off offset:88
	global_load_dword v228, v[84:85], off offset:96
	global_load_dword v229, v[84:85], off offset:104
	global_load_dword v230, v[84:85], off offset:112
	global_load_dword v231, v[84:85], off offset:120
	s_waitcnt vmcnt(0)
	v_mul_f32_e32 v200, v200, v216
	v_mul_f32_e32 v201, v201, v217
	v_mul_f32_e32 v202, v202, v218
	v_mul_f32_e32 v203, v203, v219
	v_mul_f32_e32 v204, v204, v220
	v_mul_f32_e32 v205, v205, v221
	v_mul_f32_e32 v206, v206, v222
	v_mul_f32_e32 v207, v207, v223
	v_mul_f32_e32 v208, v208, v224
	v_mul_f32_e32 v209, v209, v225
	v_mul_f32_e32 v210, v210, v226
	v_mul_f32_e32 v211, v211, v227
	v_mul_f32_e32 v212, v212, v228
	v_mul_f32_e32 v213, v213, v229
	v_mul_f32_e32 v214, v214, v230
	v_mul_f32_e32 v215, v215, v231
.Ltrq_w:
	s_waitcnt vmcnt(0)
	ds_write_b32 v125, v200
	ds_write_b32 v125, v201 offset:264
	ds_write_b32 v125, v202 offset:528
	ds_write_b32 v125, v203 offset:792
	ds_write_b32 v125, v204 offset:1056
	ds_write_b32 v125, v205 offset:1320
	ds_write_b32 v125, v206 offset:1584
	ds_write_b32 v125, v207 offset:1848
	ds_write_b32 v125, v208 offset:2112
	ds_write_b32 v125, v209 offset:2376
	ds_write_b32 v125, v210 offset:2640
	ds_write_b32 v125, v211 offset:2904
	ds_write_b32 v125, v212 offset:3168
	ds_write_b32 v125, v213 offset:3432
	ds_write_b32 v125, v214 offset:3696
	ds_write_b32 v125, v215 offset:3960
	s_add_u32 s10, s10, 0x18000
	s_addc_u32 s11, s11, 0
	s_add_u32 s12, s12, 0x80
	s_addc_u32 s13, s13, 0
	v_add_u32_e32 v125, 0x1080, v125
	s_cmp_lg_u32 s10, 0x30000
	s_cbranch_scc1 .LBB0_78
	s_branch .LBB0_142

.LBB0_149:
	v_mov_b32_e32 v200, 0
	v_mov_b32_e32 v201, 0
	v_mov_b32_e32 v202, 0
	v_mov_b32_e32 v203, 0
	v_mov_b32_e32 v204, 0
	v_mov_b32_e32 v205, 0
	v_mov_b32_e32 v206, 0
	v_mov_b32_e32 v207, 0
	v_mov_b32_e32 v208, 0
	v_mov_b32_e32 v209, 0
	v_mov_b32_e32 v210, 0
	v_mov_b32_e32 v211, 0
	v_mov_b32_e32 v212, 0
	v_mov_b32_e32 v213, 0
	v_mov_b32_e32 v214, 0
	v_mov_b32_e32 v215, 0
	v_mov_b32_e32 v216, 0
	v_mov_b32_e32 v217, 0
	v_mov_b32_e32 v218, 0
	v_mov_b32_e32 v219, 0
	v_mov_b32_e32 v220, 0
	v_mov_b32_e32 v221, 0
	v_mov_b32_e32 v222, 0
	v_mov_b32_e32 v223, 0
	v_mov_b32_e32 v224, 0
	v_mov_b32_e32 v225, 0
	v_mov_b32_e32 v226, 0
	v_mov_b32_e32 v227, 0
	v_mov_b32_e32 v228, 0
	v_mov_b32_e32 v229, 0
	v_mov_b32_e32 v230, 0
	v_mov_b32_e32 v231, 0
	s_mov_b32 s10, 0x4600
	s_mov_b32 s11, 0
	s_and_saveexec_b64 s[4:5], vcc
	s_cbranch_execz .Ltr0_skip
	v_mad_i64_i32 v[54:55], s[60:61], v4, s28, v[50:51]
	global_load_dword v200, v[54:55], off
	v_lshl_add_u64 v[54:55], v[54:55], 0, s[10:11]
	global_load_dword v201, v[54:55], off
	v_lshl_add_u64 v[54:55], v[54:55], 0, s[10:11]
	global_load_dword v202, v[54:55], off
	v_lshl_add_u64 v[54:55], v[54:55], 0, s[10:11]
	global_load_dword v203, v[54:55], off
	v_lshl_add_u64 v[54:55], v[54:55], 0, s[10:11]
	global_load_dword v204, v[54:55], off
	v_lshl_add_u64 v[54:55], v[54:55], 0, s[10:11]
	global_load_dword v205, v[54:55], off
	v_lshl_add_u64 v[54:55], v[54:55], 0, s[10:11]
	global_load_dword v206, v[54:55], off
	v_lshl_add_u64 v[54:55], v[54:55], 0, s[10:11]
	global_load_dword v207, v[54:55], off
	v_lshl_add_u64 v[54:55], v[54:55], 0, s[10:11]
	global_load_dword v208, v[54:55], off
	v_lshl_add_u64 v[54:55], v[54:55], 0, s[10:11]
	global_load_dword v209, v[54:55], off
	v_lshl_add_u64 v[54:55], v[54:55], 0, s[10:11]
	global_load_dword v210, v[54:55], off
	v_lshl_add_u64 v[54:55], v[54:55], 0, s[10:11]
	global_load_dword v211, v[54:55], off
	v_lshl_add_u64 v[54:55], v[54:55], 0, s[10:11]
	global_load_dword v212, v[54:55], off
	v_lshl_add_u64 v[54:55], v[54:55], 0, s[10:11]
	global_load_dword v213, v[54:55], off
	v_lshl_add_u64 v[54:55], v[54:55], 0, s[10:11]
	global_load_dword v214, v[54:55], off
	v_lshl_add_u64 v[54:55], v[54:55], 0, s[10:11]
	global_load_dword v215, v[54:55], off
	v_lshl_add_u64 v[54:55], v[54:55], 0, s[10:11]
	global_load_dword v216, v[54:55], off
	v_lshl_add_u64 v[54:55], v[54:55], 0, s[10:11]
	global_load_dword v217, v[54:55], off
	v_lshl_add_u64 v[54:55], v[54:55], 0, s[10:11]
	global_load_dword v218, v[54:55], off
	v_lshl_add_u64 v[54:55], v[54:55], 0, s[10:11]
	global_load_dword v219, v[54:55], off
	v_lshl_add_u64 v[54:55], v[54:55], 0, s[10:11]
	global_load_dword v220, v[54:55], off
	v_lshl_add_u64 v[54:55], v[54:55], 0, s[10:11]
	global_load_dword v221, v[54:55], off
	v_lshl_add_u64 v[54:55], v[54:55], 0, s[10:11]
	global_load_dword v222, v[54:55], off
	v_lshl_add_u64 v[54:55], v[54:55], 0, s[10:11]
	global_load_dword v223, v[54:55], off
	v_lshl_add_u64 v[54:55], v[54:55], 0, s[10:11]
	global_load_dword v224, v[54:55], off
	v_lshl_add_u64 v[54:55], v[54:55], 0, s[10:11]
	global_load_dword v225, v[54:55], off
	v_lshl_add_u64 v[54:55], v[54:55], 0, s[10:11]
	global_load_dword v226, v[54:55], off
	v_lshl_add_u64 v[54:55], v[54:55], 0, s[10:11]
	global_load_dword v227, v[54:55], off
	v_lshl_add_u64 v[54:55], v[54:55], 0, s[10:11]
	global_load_dword v228, v[54:55], off
	v_lshl_add_u64 v[54:55], v[54:55], 0, s[10:11]
	global_load_dword v229, v[54:55], off
	v_lshl_add_u64 v[54:55], v[54:55], 0, s[10:11]
	global_load_dword v230, v[54:55], off
	v_lshl_add_u64 v[54:55], v[54:55], 0, s[10:11]
	global_load_dword v231, v[54:55], off
.Ltr0_skip:
	s_or_b64 exec, exec, s[4:5]
	s_waitcnt vmcnt(31)
	ds_write_b32 v52, v200
	s_waitcnt vmcnt(30)
	ds_write_b32 v52, v201 offset:264
	s_waitcnt vmcnt(29)
	ds_write_b32 v52, v202 offset:528
	s_waitcnt vmcnt(28)
	ds_write_b32 v52, v203 offset:792
	s_waitcnt vmcnt(27)
	ds_write_b32 v52, v204 offset:1056
	s_waitcnt vmcnt(26)
	ds_write_b32 v52, v205 offset:1320
	s_waitcnt vmcnt(25)
	ds_write_b32 v52, v206 offset:1584
	s_waitcnt vmcnt(24)
	ds_write_b32 v52, v207 offset:1848
	s_waitcnt vmcnt(23)
	ds_write_b32 v52, v208 offset:2112
	s_waitcnt vmcnt(22)
	ds_write_b32 v52, v209 offset:2376
	s_waitcnt vmcnt(21)
	ds_write_b32 v52, v210 offset:2640
	s_waitcnt vmcnt(20)
	ds_write_b32 v52, v211 offset:2904
	s_waitcnt vmcnt(19)
	ds_write_b32 v52, v212 offset:3168
	s_waitcnt vmcnt(18)
	ds_write_b32 v52, v213 offset:3432
	s_waitcnt vmcnt(17)
	ds_write_b32 v52, v214 offset:3696
	s_waitcnt vmcnt(16)
	ds_write_b32 v52, v215 offset:3960
	s_waitcnt vmcnt(15)
	ds_write_b32 v52, v216 offset:4224
	s_waitcnt vmcnt(14)
	ds_write_b32 v52, v217 offset:4488
	s_waitcnt vmcnt(13)
	ds_write_b32 v52, v218 offset:4752
	s_waitcnt vmcnt(12)
	ds_write_b32 v52, v219 offset:5016
	s_waitcnt vmcnt(11)
	ds_write_b32 v52, v220 offset:5280
	s_waitcnt vmcnt(10)
	ds_write_b32 v52, v221 offset:5544
	s_waitcnt vmcnt(9)
	ds_write_b32 v52, v222 offset:5808
	s_waitcnt vmcnt(8)
	ds_write_b32 v52, v223 offset:6072
	s_waitcnt vmcnt(7)
	ds_write_b32 v52, v224 offset:6336
	s_waitcnt vmcnt(6)
	ds_write_b32 v52, v225 offset:6600
	s_waitcnt vmcnt(5)
	ds_write_b32 v52, v226 offset:6864
	s_waitcnt vmcnt(4)
	ds_write_b32 v52, v227 offset:7128
	s_waitcnt vmcnt(3)
	ds_write_b32 v52, v228 offset:7392
	s_waitcnt vmcnt(2)
	ds_write_b32 v52, v229 offset:7656
	s_waitcnt vmcnt(1)
	ds_write_b32 v52, v230 offset:7920
	s_waitcnt vmcnt(0)
	ds_write_b32 v52, v231 offset:8184
	s_branch .LBB0_22
